# attention loops: accumulator rescale with single v_mul_f32 pairs instead of v_pk_mul_f32 between the MFMAs
# baseline (speedup 1.0000x reference)
.LBB0_522:
	s_cmp_lt_u32 s15, s10
	s_cselect_b32 s4, 0, s10
	s_cselect_b32 s5, s40, s7
	s_lshl_b32 s4, s4, 5
	s_sub_i32 s4, s5, s4
	s_add_i32 s30, s21, s4
	s_add_i32 s4, s11, s15
	v_add_u32_e32 v66, s30, v189
	s_cmp_lt_u32 s4, s10
	v_ashrrev_i32_e32 v67, 31, v66
	s_cselect_b32 s4, 0, s10
	v_lshlrev_b64 v[66:67], 10, v[66:67]
	s_cselect_b32 s5, s40, s7
	s_lshl_b32 s4, s4, 5
	v_add_u32_e32 v228, 0xec00, v193
	v_add_u32_e32 v229, 0x4800, v192
	v_add_u32_e32 v230, 0x6c00, v192
	v_lshl_add_u64 v[66:67], v[178:179], 0, v[66:67]
	s_sub_i32 s4, s5, s4
	s_add_i32 s5, s33, s21
	s_waitcnt vmcnt(9)
	ds_write_b128 v191, v[130:133]
	s_waitcnt vmcnt(8)
	ds_write2_b64 v192, v[134:135], v[136:137] offset1:1
	s_waitcnt vmcnt(7)
	ds_write_b128 v191, v[142:145] offset:12800
	s_waitcnt vmcnt(6)
	ds_write2_b64 v228, v[138:139], v[140:141] offset1:1
	s_waitcnt vmcnt(5)
	ds_write_b128 v191, v[150:153] offset:25600
	s_waitcnt vmcnt(4)
	ds_write2_b64 v229, v[146:147], v[148:149] offset1:1
	s_waitcnt vmcnt(3)
	ds_write_b128 v191, v[158:161] offset:38400
	s_waitcnt vmcnt(2)
	ds_write2_b64 v230, v[154:155], v[156:157] offset1:1
	s_waitcnt vmcnt(1)
	ds_write_b128 v194, v[162:165] offset:256
	s_waitcnt vmcnt(0)
	ds_write_b128 v195, v[166:169] offset:256
	s_waitcnt lgkmcnt(0)
	s_barrier
	global_load_dwordx4 v[130:133], v[66:67], off
	v_lshl_add_u64 v[66:67], s[30:31], 1, v[180:181]
	s_add_i32 s30, s5, s4
	s_add_i32 s4, s4, s21
	global_load_dwordx4 v[134:137], v[66:67], off
	v_add_u32_e32 v66, s4, v201
	s_add_i32 s4, s18, s15
	s_cmp_lt_u32 s4, s10
	v_ashrrev_i32_e32 v67, 31, v66
	s_cselect_b32 s4, 0, s10
	v_lshlrev_b64 v[66:67], 10, v[66:67]
	s_cselect_b32 s5, s40, s7
	s_lshl_b32 s4, s4, 5
	v_lshl_add_u64 v[66:67], v[178:179], 0, v[66:67]
	s_sub_i32 s4, s5, s4
	s_add_i32 s5, s39, s21
	global_load_dwordx4 v[142:145], v[66:67], off
	v_lshl_add_u64 v[66:67], s[30:31], 1, v[180:181]
	s_add_i32 s30, s5, s4
	s_add_i32 s4, s4, s21
	global_load_dwordx4 v[138:141], v[66:67], off
	v_add_u32_e32 v66, s4, v199
	s_add_i32 s4, s19, s15
	s_cmp_lt_u32 s4, s10
	v_ashrrev_i32_e32 v67, 31, v66
	s_cselect_b32 s4, 0, s10
	v_lshlrev_b64 v[66:67], 10, v[66:67]
	s_cselect_b32 s5, s40, s7
	s_lshl_b32 s4, s4, 5
	v_lshl_add_u64 v[66:67], v[178:179], 0, v[66:67]
	s_sub_i32 s4, s5, s4
	s_add_i32 s5, s20, s21
	global_load_dwordx4 v[150:153], v[66:67], off
	v_lshl_add_u64 v[66:67], s[30:31], 1, v[180:181]
	s_add_i32 s30, s5, s4
	s_add_i32 s4, s4, s21
	global_load_dwordx4 v[146:149], v[66:67], off
	v_add_u32_e32 v66, s4, v200
	v_ashrrev_i32_e32 v67, 31, v66
	v_lshlrev_b64 v[66:67], 10, v[66:67]
	v_lshl_add_u64 v[66:67], v[178:179], 0, v[66:67]
	global_load_dwordx4 v[158:161], v[66:67], off
	v_lshl_add_u64 v[66:67], s[30:31], 1, v[180:181]
	v_cmp_gt_i32_e32 vcc, s10, v197
	v_mov_b32_e32 v68, s10
	global_load_dwordx4 v[154:157], v[66:67], off
	v_cndmask_b32_e64 v66, v68, 0, vcc
	v_mov_b32_e32 v69, s7
	v_mov_b32_e32 v70, s40
	v_cndmask_b32_e32 v67, v69, v70, vcc
	v_lshlrev_b32_e32 v66, 5, v66
	v_sub_u32_e32 v66, v67, v66
	v_add3_u32 v66, v198, s21, v66
	v_ashrrev_i32_e32 v67, 31, v66
	v_lshlrev_b64 v[66:67], 7, v[66:67]
	v_lshl_add_u64 v[66:67], v[182:183], 0, v[66:67]
	global_load_dwordx4 v[162:165], v[66:67], off
	v_add_u32_e32 v66, s18, v197
	v_cmp_gt_i32_e32 vcc, s10, v66
	v_mov_b32_e32 v0, v185
	v_mov_b32_e32 v235, v184
	v_cndmask_b32_e64 v66, v68, 0, vcc
	v_cndmask_b32_e32 v67, v69, v70, vcc
	v_lshlrev_b32_e32 v66, 5, v66
	v_sub_u32_e32 v66, v67, v66
	v_add3_u32 v66, v196, s21, v66
	v_ashrrev_i32_e32 v67, 31, v66
	v_lshlrev_b64 v[66:67], 7, v[66:67]
	v_lshl_add_u64 v[66:67], v[182:183], 0, v[66:67]
	global_load_dwordx4 v[166:169], v[66:67], off
	ds_read_b128 v[66:69], v190
	ds_read_b128 v[236:239], v190 offset:32
	s_waitcnt lgkmcnt(1)
	v_mfma_f32_32x32x16_bf16 v[66:81], v[66:69], v[118:121], 0
	v_add_u32_e32 v234, 0xc800, v227
	v_add_u32_e32 v231, 0xd800, v227
	s_add_i32 s21, s21, 32
	s_add_i32 s15, s15, 1
	v_add_u32_e32 v197, 1, v197
	s_cmp_lg_u32 s33, s21
	s_waitcnt lgkmcnt(0)
	v_mfma_f32_32x32x16_bf16 v[66:81], v[236:239], v[110:113], v[66:81]
	ds_read_b128 v[236:239], v190 offset:64
	s_waitcnt lgkmcnt(0)
	v_mfma_f32_32x32x16_bf16 v[66:81], v[236:239], v[106:109], v[66:81]
	ds_read_b128 v[236:239], v190 offset:96
	s_waitcnt lgkmcnt(0)
	v_mfma_f32_32x32x16_bf16 v[66:81], v[236:239], v[102:105], v[66:81]
	ds_read_b128 v[236:239], v190 offset:128
	s_waitcnt lgkmcnt(0)
	v_mfma_f32_32x32x16_bf16 v[66:81], v[236:239], v[98:101], v[66:81]
	ds_read_b128 v[236:239], v190 offset:160
	s_waitcnt lgkmcnt(0)
	v_mfma_f32_32x32x16_bf16 v[66:81], v[236:239], v[94:97], v[66:81]
	ds_read_b128 v[236:239], v190 offset:192
	s_waitcnt lgkmcnt(0)
	v_mfma_f32_32x32x16_bf16 v[66:81], v[236:239], v[90:93], v[66:81]
	ds_read_b128 v[236:239], v190 offset:224
	s_waitcnt lgkmcnt(0)
	v_mfma_f32_32x32x16_bf16 v[66:81], v[236:239], v[86:89], v[66:81]
	ds_read_b128 v[236:239], v190 offset:256
	s_waitcnt lgkmcnt(0)
	v_mfma_f32_32x32x16_bf16 v[66:81], v[236:239], v[122:125], v[66:81]
	ds_read_b128 v[236:239], v190 offset:288
	s_waitcnt lgkmcnt(0)
	v_mfma_f32_32x32x16_bf16 v[66:81], v[236:239], v[114:117], v[66:81]
	ds_read_b128 v[236:239], v190 offset:320
	s_waitcnt lgkmcnt(0)
	v_mfma_f32_32x32x16_bf16 v[66:81], v[236:239], v[126:129], v[66:81]
	ds_read_b128 v[236:239], v190 offset:352
	s_waitcnt lgkmcnt(0)
	v_mfma_f32_32x32x16_bf16 v[66:81], v[236:239], v[82:85], v[66:81]
	s_nop 11
	v_max_f32_e32 v184, v67, v67
	v_max_f32_e32 v185, v66, v66
	v_max_f32_e32 v184, v185, v184
	v_max3_f32 v184, v184, v68, v69
	v_max3_f32 v184, v184, v70, v71
	v_max3_f32 v184, v184, v72, v73
	v_max3_f32 v184, v184, v74, v75
	v_max3_f32 v184, v184, v76, v77
	v_max3_f32 v184, v184, v78, v79
	v_max3_f32 v184, v184, v80, v81
	ds_bpermute_b32 v185, v187, v184
	s_waitcnt lgkmcnt(0)
	v_max3_f32 v185, v0, v184, v185
	v_mov_b32_e32 v184, v81
	v_pk_mul_f32 v[232:233], v[184:185], s[26:27] op_sel_hi:[1,0]
	v_sub_f32_e32 v0, v0, v185
	v_fma_f32 v66, v66, s26, -v233
	v_exp_f32_e32 v66, v66
	v_fma_f32 v67, v67, s26, -v233
	v_exp_f32_e32 v67, v67
	v_fma_f32 v68, v68, s26, -v233
	v_exp_f32_e32 v68, v68
	v_fma_f32 v69, v69, s26, -v233
	v_exp_f32_e32 v69, v69
	v_fma_f32 v70, v70, s26, -v233
	v_exp_f32_e32 v70, v70
	v_fma_f32 v71, v71, s26, -v233
	v_add_f32_e32 v184, 0, v66
	v_exp_f32_e32 v71, v71
	v_fma_f32 v72, v72, s26, -v233
	v_add_f32_e32 v184, v67, v184
	v_exp_f32_e32 v72, v72
	v_fma_f32 v73, v73, s26, -v233
	v_add_f32_e32 v184, v68, v184
	v_exp_f32_e32 v73, v73
	v_fma_f32 v74, v74, s26, -v233
	v_add_f32_e32 v184, v69, v184
	v_exp_f32_e32 v74, v74
	v_fma_f32 v75, v75, s26, -v233
	v_add_f32_e32 v184, v70, v184
	v_exp_f32_e32 v75, v75
	v_fma_f32 v76, v76, s26, -v233
	v_add_f32_e32 v184, v71, v184
	v_exp_f32_e32 v76, v76
	v_fma_f32 v77, v77, s26, -v233
	v_add_f32_e32 v184, v72, v184
	v_exp_f32_e32 v77, v77
	v_fma_f32 v78, v78, s26, -v233
	v_add_f32_e32 v184, v73, v184
	v_exp_f32_e32 v78, v78
	v_fma_f32 v79, v79, s26, -v233
	v_add_f32_e32 v184, v74, v184
	v_exp_f32_e32 v79, v79
	v_fma_f32 v80, v80, s26, -v233
	v_add_f32_e32 v184, v75, v184
	v_exp_f32_e32 v80, v80
	v_sub_f32_e32 v81, v232, v233
	v_add_f32_e32 v184, v76, v184
	v_exp_f32_e32 v81, v81
	v_add_f32_e32 v184, v77, v184
	v_add_f32_e32 v184, v78, v184
	v_mul_f32_e32 v0, 0x3dd53b94, v0
	v_add_f32_e32 v184, v79, v184
	v_exp_f32_e32 v0, v0
	v_add_f32_e32 v184, v80, v184
	v_add_f32_e32 v184, v81, v184
	v_cvt_pk_bf16_f32 v66, v66, v67
	v_cvt_pk_bf16_f32 v67, v68, v69
	v_cvt_pk_bf16_f32 v68, v70, v71
	v_cvt_pk_bf16_f32 v69, v72, v73
	v_cvt_pk_bf16_f32 v70, v74, v75
	v_cvt_pk_bf16_f32 v71, v76, v77
	v_cvt_pk_bf16_f32 v72, v78, v79
	v_cvt_pk_bf16_f32 v73, v80, v81
	ds_read2_b64 v[74:77], v234 offset1:2
	ds_read2_b64 v[78:81], v234 offset0:4 offset1:6
	v_mul_f32_e32 v16, v0, v16
	v_mul_f32_e32 v17, v0, v17
	v_mul_f32_e32 v14, v0, v14
	v_mul_f32_e32 v15, v0, v15
	v_mul_f32_e32 v12, v0, v12
	v_mul_f32_e32 v13, v0, v13
	v_mul_f32_e32 v10, v0, v10
	v_mul_f32_e32 v11, v0, v11
	v_mul_f32_e32 v8, v0, v8
	v_mul_f32_e32 v9, v0, v9
	v_mul_f32_e32 v6, v0, v6
	v_mul_f32_e32 v7, v0, v7
	v_mul_f32_e32 v4, v0, v4
	v_mul_f32_e32 v5, v0, v5
	v_mul_f32_e32 v2, v0, v2
	v_mul_f32_e32 v3, v0, v3
	v_add_u32_e32 v233, 0xd000, v227
	v_mul_f32_e32 v48, v0, v48
	v_mul_f32_e32 v49, v0, v49
	s_waitcnt lgkmcnt(1)
	v_mfma_f32_32x32x16_bf16 v[2:17], v[74:77], v[66:69], v[2:17]
	ds_read2_b64 v[74:77], v233 offset0:32 offset1:34
	v_mul_f32_e64 v46, v46, v0
	v_mul_f32_e64 v47, v47, v0
	v_mul_f32_e64 v44, v44, v0
	v_mul_f32_e64 v45, v45, v0
	v_mul_f32_e32 v42, v0, v42
	v_mul_f32_e32 v43, v0, v43
	v_mul_f32_e32 v40, v0, v40
	v_mul_f32_e32 v41, v0, v41
	v_mul_f32_e32 v38, v0, v38
	v_mul_f32_e32 v39, v0, v39
	v_mul_f32_e32 v36, v0, v36
	v_mul_f32_e32 v37, v0, v37
	v_mul_f32_e32 v34, v0, v34
	v_mul_f32_e32 v35, v0, v35
	v_mul_f32_e32 v64, v0, v64
	v_mul_f32_e32 v65, v0, v65
	v_mul_f32_e32 v62, v0, v62
	v_mul_f32_e32 v63, v0, v63
	s_waitcnt lgkmcnt(0)
	v_mfma_f32_32x32x16_bf16 v[34:49], v[74:77], v[66:69], v[34:49]
	ds_read2_b64 v[74:77], v233 offset0:36 offset1:38
	v_mul_f32_e64 v60, v60, v0
	v_mul_f32_e64 v61, v61, v0
	v_mul_f32_e64 v58, v58, v0
	v_mul_f32_e64 v59, v59, v0
	v_mul_f32_e32 v56, v0, v56
	v_mul_f32_e32 v57, v0, v57
	v_mul_f32_e32 v54, v0, v54
	v_mul_f32_e32 v55, v0, v55
	v_mul_f32_e32 v52, v0, v52
	v_mul_f32_e32 v53, v0, v53
	v_mul_f32_e32 v50, v0, v50
	v_mul_f32_e32 v51, v0, v51
	s_waitcnt lgkmcnt(0)
	v_mfma_f32_32x32x16_bf16 v[34:49], v[74:77], v[70:73], v[34:49]
	ds_read2_b64 v[74:77], v231 offset0:64 offset1:66
	v_add_u32_e32 v232, 0xe000, v227
	v_mul_f32_e64 v32, v32, v0
	v_mul_f32_e64 v33, v33, v0
	v_mul_f32_e64 v30, v30, v0
	v_mul_f32_e64 v31, v31, v0
	v_mul_f32_e32 v28, v0, v28
	v_mul_f32_e32 v29, v0, v29
	v_mul_f32_e32 v26, v0, v26
	v_mul_f32_e32 v27, v0, v27
	v_mul_f32_e32 v24, v0, v24
	v_mul_f32_e32 v25, v0, v25
	s_waitcnt lgkmcnt(0)
	v_mfma_f32_32x32x16_bf16 v[50:65], v[74:77], v[66:69], v[50:65]
	ds_read2_b64 v[74:77], v231 offset0:68 offset1:70
	v_mul_f32_e64 v22, v22, v0
	v_mul_f32_e64 v23, v23, v0
	v_mul_f32_e64 v20, v20, v0
	v_mul_f32_e64 v21, v21, v0
	v_mul_f32_e32 v18, v0, v18
	v_mul_f32_e32 v19, v0, v19
	v_fmac_f32_e32 v184, v235, v0
	s_waitcnt lgkmcnt(0)
	v_mfma_f32_32x32x16_bf16 v[50:65], v[74:77], v[70:73], v[50:65]
	ds_read2_b64 v[74:77], v232 offset0:96 offset1:98
	s_waitcnt lgkmcnt(0)
	v_mfma_f32_32x32x16_bf16 v[18:33], v[74:77], v[66:69], v[18:33]
	ds_read2_b64 v[66:69], v232 offset0:100 offset1:102
	s_waitcnt lgkmcnt(0)
	s_barrier
	v_mfma_f32_32x32x16_bf16 v[2:17], v[78:81], v[70:73], v[2:17]
	v_mfma_f32_32x32x16_bf16 v[18:33], v[66:69], v[70:73], v[18:33]
	s_cbranch_scc1 .LBB0_522
	s_waitcnt vmcnt(9)
	ds_write_b128 v191, v[130:133]
	s_waitcnt vmcnt(8)
	ds_write2_b64 v192, v[134:135], v[136:137] offset1:1
	s_waitcnt vmcnt(7)
	ds_write_b128 v191, v[142:145] offset:12800
	s_waitcnt vmcnt(6)
	ds_write2_b64 v228, v[138:139], v[140:141] offset1:1
	s_waitcnt vmcnt(5)
	ds_write_b128 v191, v[150:153] offset:25600
	s_waitcnt vmcnt(4)
	ds_write2_b64 v229, v[146:147], v[148:149] offset1:1
	s_waitcnt vmcnt(3)
	ds_write_b128 v191, v[158:161] offset:38400
	s_waitcnt vmcnt(2)
	ds_write2_b64 v230, v[154:155], v[156:157] offset1:1
	s_waitcnt vmcnt(1)
	ds_write_b128 v194, v[162:165] offset:256
	s_waitcnt vmcnt(0)
	ds_write_b128 v195, v[166:169] offset:256
	s_waitcnt lgkmcnt(0)
	s_barrier
	ds_read_b128 v[66:69], v190
	ds_read_b128 v[130:133], v190 offset:32
	s_waitcnt lgkmcnt(1)
	v_mfma_f32_32x32x16_bf16 v[66:81], v[66:69], v[118:121], 0
	v_readlane_b32 s4, v253, 17
	s_mov_b32 s7, 0xf149f2ca
	s_mov_b32 s39, s31
	s_waitcnt lgkmcnt(0)
	v_mfma_f32_32x32x16_bf16 v[66:81], v[130:133], v[110:113], v[66:81]
	ds_read_b128 v[110:113], v190 offset:64
	ds_read_b128 v[118:121], v190 offset:96
	s_waitcnt lgkmcnt(1)
	v_mfma_f32_32x32x16_bf16 v[66:81], v[110:113], v[106:109], v[66:81]
	v_ashrrev_i32_e32 v110, 6, v188
	s_waitcnt lgkmcnt(0)
	v_mfma_f32_32x32x16_bf16 v[66:81], v[118:121], v[102:105], v[66:81]
	ds_read_b128 v[102:105], v190 offset:128
	ds_read_b128 v[106:109], v190 offset:160
	s_waitcnt lgkmcnt(1)
	v_mfma_f32_32x32x16_bf16 v[66:81], v[102:105], v[98:101], v[66:81]
	s_waitcnt lgkmcnt(0)
	v_mfma_f32_32x32x16_bf16 v[66:81], v[106:109], v[94:97], v[66:81]
	ds_read_b128 v[94:97], v190 offset:192
	ds_read_b128 v[98:101], v190 offset:224
	s_waitcnt lgkmcnt(1)
	v_mfma_f32_32x32x16_bf16 v[66:81], v[94:97], v[90:93], v[66:81]
	s_waitcnt lgkmcnt(0)
	v_mfma_f32_32x32x16_bf16 v[66:81], v[98:101], v[86:89], v[66:81]
	ds_read_b128 v[86:89], v190 offset:256
	ds_read_b128 v[90:93], v190 offset:288
	s_waitcnt lgkmcnt(1)
	v_mfma_f32_32x32x16_bf16 v[66:81], v[86:89], v[122:125], v[66:81]
	s_waitcnt lgkmcnt(0)
	v_mfma_f32_32x32x16_bf16 v[66:81], v[90:93], v[114:117], v[66:81]
	ds_read_b128 v[90:93], v190 offset:320
	ds_read_b128 v[86:89], v190 offset:352
	s_waitcnt lgkmcnt(1)
	v_mfma_f32_32x32x16_bf16 v[66:81], v[90:93], v[126:129], v[66:81]
	ds_read2_b64 v[90:93], v234 offset1:2
	ds_read2_b64 v[94:97], v234 offset0:4 offset1:6
	ds_read2_b64 v[98:101], v233 offset0:32 offset1:34
	s_waitcnt lgkmcnt(3)
	v_mfma_f32_32x32x16_bf16 v[66:81], v[86:89], v[82:85], v[66:81]
	ds_read2_b64 v[84:87], v233 offset0:36 offset1:38
	ds_read2_b64 v[102:105], v231 offset0:64 offset1:66
	s_nop 9
	v_max_f32_e32 v0, v67, v67
	v_max_f32_e32 v82, v66, v66
	v_max_f32_e32 v0, v82, v0
	v_max3_f32 v0, v0, v68, v69
	v_max3_f32 v0, v0, v70, v71
	v_max3_f32 v0, v0, v72, v73
	v_max3_f32 v0, v0, v74, v75
	v_max3_f32 v0, v0, v76, v77
	v_max3_f32 v0, v0, v78, v79
	v_max3_f32 v0, v0, v80, v81
	ds_bpermute_b32 v83, v187, v0
	v_mov_b32_e32 v88, v81
	v_and_b32_e32 v82, 1, v110
	s_waitcnt lgkmcnt(0)
	v_max3_f32 v89, v185, v0, v83
	v_sub_f32_e32 v0, v185, v89
	v_pk_mul_f32 v[106:107], v[88:89], s[26:27] op_sel_hi:[1,0]
	v_mul_f32_e32 v0, 0x3dd53b94, v0
	v_fma_f32 v66, v66, s26, -v107
	v_fma_f32 v67, v67, s26, -v107
	v_fma_f32 v68, v68, s26, -v107
	v_fma_f32 v69, v69, s26, -v107
	v_fma_f32 v70, v70, s26, -v107
	v_fma_f32 v71, v71, s26, -v107
	v_fma_f32 v72, v72, s26, -v107
	v_fma_f32 v73, v73, s26, -v107
	v_exp_f32_e32 v0, v0
	v_exp_f32_e32 v88, v66
	v_exp_f32_e32 v111, v67
	v_exp_f32_e32 v112, v68
	v_exp_f32_e32 v113, v69
	v_exp_f32_e32 v114, v70
	v_exp_f32_e32 v115, v71
	v_exp_f32_e32 v116, v72
	v_exp_f32_e32 v117, v73
	v_fma_f32 v74, v74, s26, -v107
	v_fma_f32 v75, v75, s26, -v107
	v_fma_f32 v76, v76, s26, -v107
	v_fma_f32 v77, v77, s26, -v107
	v_fma_f32 v78, v78, s26, -v107
	v_fma_f32 v79, v79, s26, -v107
	v_fma_f32 v80, v80, s26, -v107
	v_sub_f32_e32 v83, v106, v107
	v_exp_f32_e32 v118, v74
	v_exp_f32_e32 v119, v75
	v_exp_f32_e32 v120, v76
	v_exp_f32_e32 v121, v77
	v_exp_f32_e32 v122, v78
	v_exp_f32_e32 v123, v79
	v_exp_f32_e32 v124, v80
	v_pk_mul_f32 v[80:81], v[16:17], v[0:1] op_sel_hi:[1,0]
	v_pk_mul_f32 v[78:79], v[14:15], v[0:1] op_sel_hi:[1,0]
	v_pk_mul_f32 v[76:77], v[12:13], v[0:1] op_sel_hi:[1,0]
	v_pk_mul_f32 v[74:75], v[10:11], v[0:1] op_sel_hi:[1,0]
	v_pk_mul_f32 v[72:73], v[8:9], v[0:1] op_sel_hi:[1,0]
	v_pk_mul_f32 v[70:71], v[6:7], v[0:1] op_sel_hi:[1,0]
	v_pk_mul_f32 v[68:69], v[4:5], v[0:1] op_sel_hi:[1,0]
	v_pk_mul_f32 v[66:67], v[2:3], v[0:1] op_sel_hi:[1,0]
	v_pk_mul_f32 v[16:17], v[48:49], v[0:1] op_sel_hi:[1,0]
	v_cvt_pk_bf16_f32 v106, v88, v111
	v_cvt_pk_bf16_f32 v107, v112, v113
	v_cvt_pk_bf16_f32 v108, v114, v115
	v_cvt_pk_bf16_f32 v109, v116, v117
	v_pk_mul_f32 v[14:15], v[46:47], v[0:1] op_sel_hi:[1,0]
	v_pk_mul_f32 v[12:13], v[44:45], v[0:1] op_sel_hi:[1,0]
	v_pk_mul_f32 v[10:11], v[42:43], v[0:1] op_sel_hi:[1,0]
	v_pk_mul_f32 v[8:9], v[40:41], v[0:1] op_sel_hi:[1,0]
	v_pk_mul_f32 v[6:7], v[38:39], v[0:1] op_sel_hi:[1,0]
	v_pk_mul_f32 v[4:5], v[36:37], v[0:1] op_sel_hi:[1,0]
	v_pk_mul_f32 v[2:3], v[34:35], v[0:1] op_sel_hi:[1,0]
	v_pk_mul_f32 v[48:49], v[64:65], v[0:1] op_sel_hi:[1,0]
	v_pk_mul_f32 v[46:47], v[62:63], v[0:1] op_sel_hi:[1,0]
	v_pk_mul_f32 v[44:45], v[60:61], v[0:1] op_sel_hi:[1,0]
	v_pk_mul_f32 v[42:43], v[58:59], v[0:1] op_sel_hi:[1,0]
	v_pk_mul_f32 v[40:41], v[56:57], v[0:1] op_sel_hi:[1,0]
	v_pk_mul_f32 v[38:39], v[54:55], v[0:1] op_sel_hi:[1,0]
	v_pk_mul_f32 v[36:37], v[52:53], v[0:1] op_sel_hi:[1,0]
	v_pk_mul_f32 v[34:35], v[50:51], v[0:1] op_sel_hi:[1,0]
	ds_read2_b64 v[50:53], v231 offset0:68 offset1:70
	v_add_f32_e32 v54, 0, v88
	v_mfma_f32_32x32x16_bf16 v[34:49], v[102:105], v[106:109], v[34:49]
	v_add_f32_e32 v54, v111, v54
	v_exp_f32_e32 v83, v83
	v_add_f32_e32 v54, v112, v54
	v_add_f32_e32 v54, v113, v54
	v_add_f32_e32 v58, v114, v54
	ds_read2_b64 v[54:57], v232 offset0:96 offset1:98
	v_cvt_pk_bf16_f32 v62, v118, v119
	v_cvt_pk_bf16_f32 v63, v120, v121
	v_cvt_pk_bf16_f32 v64, v122, v123
	v_cvt_pk_bf16_f32 v65, v124, v83
	v_mfma_f32_32x32x16_bf16 v[66:81], v[90:93], v[106:109], v[66:81]
	v_mul_f32_e64 v32, v32, v0
	v_mul_f32_e64 v33, v33, v0
	v_mul_f32_e64 v30, v30, v0
	v_mul_f32_e64 v31, v31, v0
	v_mul_f32_e64 v28, v28, v0
	v_mul_f32_e64 v29, v29, v0
	v_pk_mul_f32 v[26:27], v[26:27], v[0:1] op_sel_hi:[1,0]
	v_pk_mul_f32 v[24:25], v[24:25], v[0:1] op_sel_hi:[1,0]
	v_pk_mul_f32 v[22:23], v[22:23], v[0:1] op_sel_hi:[1,0]
	v_pk_mul_f32 v[20:21], v[20:21], v[0:1] op_sel_hi:[1,0]
	s_waitcnt lgkmcnt(1)
	v_mfma_f32_32x32x16_bf16 v[34:49], v[50:53], v[62:65], v[34:49]
	v_add_f32_e32 v50, v115, v58
	v_add_f32_e32 v50, v116, v50
	v_add_f32_e32 v50, v117, v50
	v_add_f32_e32 v50, v118, v50
	v_add_f32_e32 v50, v119, v50
	v_pk_mul_f32 v[18:19], v[18:19], v[0:1] op_sel_hi:[1,0]
	v_add_f32_e32 v58, v120, v50
	ds_read2_b64 v[50:53], v232 offset0:100 offset1:102
	s_waitcnt lgkmcnt(1)
	v_mfma_f32_32x32x16_bf16 v[18:33], v[54:57], v[106:109], v[18:33]
	v_add_f32_e32 v54, v121, v58
	v_add_f32_e32 v54, v122, v54
	v_add_f32_e32 v54, v123, v54
	v_add_f32_e32 v54, v124, v54
	v_add_f32_e32 v54, v83, v54
	v_fmac_f32_e32 v54, v184, v0
	ds_bpermute_b32 v0, v187, v54
	v_mfma_f32_32x32x16_bf16 v[2:17], v[98:101], v[106:109], v[2:17]
	s_waitcnt lgkmcnt(0)
	s_barrier
	v_add_f32_e32 v0, v54, v0
	v_mfma_f32_32x32x16_bf16 v[66:81], v[94:97], v[62:65], v[66:81]
	v_mfma_f32_32x32x16_bf16 v[18:33], v[50:53], v[62:65], v[18:33]
	v_lshlrev_b32_e32 v50, 9, v110
	v_lshlrev_b32_e32 v51, 2, v186
	v_add3_u32 v50, s4, v50, v51
	ds_write2st64_b32 v50, v89, v0 offset1:1
	v_lshlrev_b32_e32 v0, 14, v110
	v_add3_u32 v0, 0, v0, v51
	v_mfma_f32_32x32x16_bf16 v[2:17], v[84:87], v[62:65], v[2:17]
	s_nop 3
	ds_write2st64_b32 v0, v66, v67 offset1:1
	ds_write2st64_b32 v0, v68, v69 offset0:2 offset1:3
	ds_write2st64_b32 v0, v70, v71 offset0:4 offset1:5
	ds_write2st64_b32 v0, v72, v73 offset0:6 offset1:7
	ds_write2st64_b32 v0, v74, v75 offset0:8 offset1:9
	ds_write2st64_b32 v0, v76, v77 offset0:10 offset1:11
	ds_write2st64_b32 v0, v78, v79 offset0:12 offset1:13
	ds_write2st64_b32 v0, v80, v81 offset0:14 offset1:15
	ds_write2st64_b32 v0, v2, v3 offset0:16 offset1:17
	ds_write2st64_b32 v0, v4, v5 offset0:18 offset1:19
	ds_write2st64_b32 v0, v6, v7 offset0:20 offset1:21
	ds_write2st64_b32 v0, v8, v9 offset0:22 offset1:23
	ds_write2st64_b32 v0, v10, v11 offset0:24 offset1:25
	ds_write2st64_b32 v0, v12, v13 offset0:26 offset1:27
	ds_write2st64_b32 v0, v14, v15 offset0:28 offset1:29
	ds_write2st64_b32 v0, v16, v17 offset0:30 offset1:31
	ds_write2st64_b32 v0, v34, v35 offset0:32 offset1:33
	ds_write2st64_b32 v0, v36, v37 offset0:34 offset1:35
	ds_write2st64_b32 v0, v38, v39 offset0:36 offset1:37
	ds_write2st64_b32 v0, v40, v41 offset0:38 offset1:39
	ds_write2st64_b32 v0, v42, v43 offset0:40 offset1:41
	ds_write2st64_b32 v0, v44, v45 offset0:42 offset1:43
	ds_write2st64_b32 v0, v46, v47 offset0:44 offset1:45
	ds_write2st64_b32 v0, v48, v49 offset0:46 offset1:47
	ds_write2st64_b32 v0, v18, v19 offset0:48 offset1:49
	ds_write2st64_b32 v0, v20, v21 offset0:50 offset1:51
	ds_write2st64_b32 v0, v22, v23 offset0:52 offset1:53
	ds_write2st64_b32 v0, v24, v25 offset0:54 offset1:55
	ds_write2st64_b32 v0, v26, v27 offset0:56 offset1:57
	ds_write2st64_b32 v0, v28, v29 offset0:58 offset1:59
	ds_write2st64_b32 v0, v30, v31 offset0:60 offset1:61
	ds_write2st64_b32 v0, v32, v33 offset0:62 offset1:63
	v_lshlrev_b32_e32 v0, 9, v82
	v_add3_u32 v0, s4, v0, v51
	s_waitcnt lgkmcnt(0)
	s_barrier
	ds_read2st64_b32 v[4:5], v0 offset1:1
	ds_read2st64_b32 v[6:7], v0 offset0:4 offset1:5
	ds_read2st64_b32 v[8:9], v0 offset0:8 offset1:9
	ds_read2st64_b32 v[10:11], v0 offset0:12 offset1:13
	s_lshl_b64 s[4:5], s[38:39], 11
	s_waitcnt lgkmcnt(2)
	v_max3_f32 v0, v4, s7, v6
	s_add_u32 s7, s80, s4
	s_waitcnt lgkmcnt(0)
	v_max3_f32 v0, v0, v8, v10
	v_sub_f32_e32 v2, v4, v0
	v_mul_f32_e32 v2, 0x3dd53b94, v2
	v_exp_f32_e32 v3, v2
	v_sub_f32_e32 v2, v6, v0
	v_mul_f32_e32 v2, 0x3dd53b94, v2
	v_exp_f32_e32 v2, v2
	v_mov_b32_e32 v4, v7
	s_addc_u32 s10, s81, s5
	v_pk_mul_f32 v[6:7], v[4:5], v[2:3]
	v_sub_f32_e32 v4, v8, v0
	v_sub_f32_e32 v0, v10, v0
	v_mul_f32_e32 v4, 0x3dd53b94, v4
	v_mul_f32_e32 v0, 0x3dd53b94, v0
	v_exp_f32_e32 v5, v4
	v_exp_f32_e32 v4, v0
	v_add_f32_e32 v0, 0, v7
	v_mov_b32_e32 v8, v11
	v_add_f32_e32 v0, v6, v0
	v_pk_mul_f32 v[6:7], v[8:9], v[4:5]
	s_nop 0
	v_add_f32_e32 v0, v7, v0
	v_add_f32_e32 v0, v6, v0
	v_div_scale_f32 v6, s[4:5], v0, v0, 1.0
	v_rcp_f32_e32 v7, v6
	s_lshl_b32 s4, s14, 1
	s_add_u32 s38, s7, s4
	s_addc_u32 s39, s10, 0
	v_fma_f32 v8, -v6, v7, 1.0
	v_fmac_f32_e32 v7, v8, v7
	v_div_scale_f32 v8, vcc, 1.0, v0, 1.0
	v_mul_f32_e32 v9, v8, v7
	v_fma_f32 v10, -v6, v9, v8
	v_fmac_f32_e32 v9, v10, v7
	v_fma_f32 v6, -v6, v9, v8
	v_div_fmas_f32 v6, v6, v7, v9
	v_div_fixup_f32 v0, v6, v0, 1.0
	v_lshl_add_u32 v6, v82, 14, 0
	v_lshlrev_b32_e32 v7, 12, v177
	v_add3_u32 v7, v6, v7, v51
	ds_read2st64_b32 v[8:9], v7 offset1:1
	ds_read2st64_b32 v[10:11], v7 offset0:128 offset1:129
	v_mov_b32_e32 v6, v3
	v_add_u32_e32 v24, 0x10000, v7
	v_add_u32_e32 v25, 0x18000, v7
	v_add_u32_e32 v27, 0x10100, v7
	v_add_u32_e32 v28, 0x18100, v7
	ds_read2st64_b32 v[12:13], v7 offset0:2 offset1:3
	ds_read2st64_b32 v[14:15], v7 offset0:4 offset1:5
	ds_read2st64_b32 v[16:17], v7 offset0:6 offset1:7
	s_waitcnt lgkmcnt(4)
	v_pk_fma_f32 v[8:9], v[8:9], v[6:7], 0 op_sel_hi:[1,0,0]
	v_add_u32_e32 v31, 0x18300, v7
	ds_read2st64_b32 v[18:19], v7 offset0:130 offset1:131
	ds_read2st64_b32 v[20:21], v7 offset0:132 offset1:133
	ds_read2st64_b32 v[22:23], v7 offset0:134 offset1:135
	s_waitcnt lgkmcnt(6)
	v_pk_fma_f32 v[8:9], v[10:11], v[2:3], v[8:9] op_sel_hi:[1,0,1]
	v_mov_b32_e32 v10, v5
	v_add_u32_e32 v3, 0x10200, v7
	v_add_u32_e32 v5, 0x18200, v7
	v_add_u32_e32 v11, 0x10300, v7
	ds_read_b32 v24, v24
	ds_read_b32 v26, v25
	ds_read_b32 v25, v27
	ds_read_b32 v27, v28
	ds_read_b32 v28, v3
	ds_read_b32 v30, v5
	ds_read_b32 v29, v11
	ds_read_b32 v31, v31
	s_waitcnt lgkmcnt(13)
	v_pk_fma_f32 v[12:13], v[6:7], v[12:13], 0 op_sel_hi:[0,1,0]
	s_waitcnt lgkmcnt(5)
	v_pk_fma_f32 v[8:9], v[10:11], v[24:25], v[8:9] op_sel_hi:[0,1,1]
	v_pk_fma_f32 v[12:13], v[2:3], v[18:19], v[12:13] op_sel_hi:[0,1,1]
	v_add_u32_e32 v3, 0x10400, v7
	v_pk_fma_f32 v[14:15], v[6:7], v[14:15], 0 op_sel_hi:[0,1,0]
	s_waitcnt lgkmcnt(4)
	v_pk_fma_f32 v[8:9], v[4:5], v[26:27], v[8:9] op_sel_hi:[0,1,1]
	s_waitcnt lgkmcnt(1)
	v_pk_fma_f32 v[12:13], v[10:11], v[28:29], v[12:13] op_sel_hi:[0,1,1]
	v_add_u32_e32 v11, 0x10500, v7
	v_add_u32_e32 v24, 0x18500, v7
	v_pk_fma_f32 v[14:15], v[2:3], v[20:21], v[14:15] op_sel_hi:[0,1,1]
	v_add_u32_e32 v25, 0x10600, v7
	v_add_u32_e32 v26, 0x18600, v7
	v_add_u32_e32 v27, 0x10700, v7
	s_waitcnt lgkmcnt(0)
	v_pk_fma_f32 v[12:13], v[4:5], v[30:31], v[12:13] op_sel_hi:[0,1,1]
	v_add_u32_e32 v5, 0x18400, v7
	v_add_u32_e32 v28, 0x18700, v7
	ds_read_b32 v18, v3
	ds_read_b32 v20, v5
	ds_read_b32 v19, v11
	ds_read_b32 v21, v24
	ds_read_b32 v24, v25
	ds_read_b32 v26, v26
	ds_read_b32 v25, v27
	ds_read_b32 v27, v28
	s_waitcnt lgkmcnt(5)
	v_pk_fma_f32 v[14:15], v[10:11], v[18:19], v[14:15] op_sel_hi:[0,1,1]
	s_waitcnt lgkmcnt(4)
	v_pk_fma_f32 v[14:15], v[4:5], v[20:21], v[14:15] op_sel_hi:[0,1,1]
	ds_read2st64_b32 v[18:19], v7 offset0:8 offset1:9
	ds_read2st64_b32 v[20:21], v7 offset0:136 offset1:137
	v_pk_fma_f32 v[16:17], v[6:7], v[16:17], 0 op_sel_hi:[0,1,0]
	v_pk_fma_f32 v[16:17], v[2:3], v[22:23], v[16:17] op_sel_hi:[0,1,1]
	s_waitcnt lgkmcnt(3)
	v_pk_fma_f32 v[16:17], v[10:11], v[24:25], v[16:17] op_sel_hi:[0,1,1]
	s_waitcnt lgkmcnt(2)
	v_pk_fma_f32 v[16:17], v[4:5], v[26:27], v[16:17] op_sel_hi:[0,1,1]
	v_add_u32_e32 v3, 0x10800, v7
	v_add_u32_e32 v35, 0x18900, v7
	ds_read2st64_b32 v[22:23], v7 offset0:10 offset1:11
	ds_read2st64_b32 v[24:25], v7 offset0:12 offset1:13
	ds_read2st64_b32 v[26:27], v7 offset0:14 offset1:15
	s_waitcnt lgkmcnt(4)
	v_pk_fma_f32 v[18:19], v[6:7], v[18:19], 0 op_sel_hi:[0,1,0]
	v_add_u32_e32 v36, 0x10a00, v7
	v_add_u32_e32 v37, 0x18a00, v7
	v_add_u32_e32 v39, 0x10b00, v7
	v_add_u32_e32 v5, 0x18800, v7
	v_add_u32_e32 v11, 0x10900, v7
	ds_read2st64_b32 v[28:29], v7 offset0:138 offset1:139
	ds_read2st64_b32 v[30:31], v7 offset0:140 offset1:141
	ds_read2st64_b32 v[32:33], v7 offset0:142 offset1:143
	s_waitcnt lgkmcnt(6)
	v_pk_fma_f32 v[18:19], v[2:3], v[20:21], v[18:19] op_sel_hi:[0,1,1]
	v_add_u32_e32 v40, 0x18b00, v7
	ds_read_b32 v20, v3
	ds_read_b32 v34, v5
	ds_read_b32 v21, v11
	ds_read_b32 v35, v35
	ds_read_b32 v36, v36
	ds_read_b32 v38, v37
	ds_read_b32 v37, v39
	ds_read_b32 v39, v40
	s_waitcnt lgkmcnt(5)
	v_pk_fma_f32 v[18:19], v[10:11], v[20:21], v[18:19] op_sel_hi:[0,1,1]
	v_pk_fma_f32 v[20:21], v[6:7], v[22:23], 0 op_sel_hi:[0,1,0]
	v_pk_fma_f32 v[20:21], v[2:3], v[28:29], v[20:21] op_sel_hi:[0,1,1]
	v_add_u32_e32 v3, 0x10c00, v7
	v_pk_fma_f32 v[22:23], v[6:7], v[24:25], 0 op_sel_hi:[0,1,0]
	s_waitcnt lgkmcnt(4)
	v_pk_fma_f32 v[18:19], v[4:5], v[34:35], v[18:19] op_sel_hi:[0,1,1]
	s_waitcnt lgkmcnt(1)
	v_pk_fma_f32 v[20:21], v[10:11], v[36:37], v[20:21] op_sel_hi:[0,1,1]
	v_add_u32_e32 v29, 0x18d00, v7
	v_pk_fma_f32 v[22:23], v[2:3], v[30:31], v[22:23] op_sel_hi:[0,1,1]
	v_add_u32_e32 v30, 0x10e00, v7
	v_add_u32_e32 v31, 0x18e00, v7
	v_add_u32_e32 v35, 0x10f00, v7
	s_waitcnt lgkmcnt(0)
	v_pk_fma_f32 v[20:21], v[4:5], v[38:39], v[20:21] op_sel_hi:[0,1,1]
	v_add_u32_e32 v5, 0x18c00, v7
	v_add_u32_e32 v11, 0x10d00, v7
	v_add_u32_e32 v7, 0x18f00, v7
	ds_read_b32 v24, v3
	ds_read_b32 v28, v5
	ds_read_b32 v25, v11
	ds_read_b32 v29, v29
	ds_read_b32 v30, v30
	ds_read_b32 v34, v31
	ds_read_b32 v31, v35
	ds_read_b32 v35, v7
	v_pk_fma_f32 v[6:7], v[6:7], v[26:27], 0 op_sel_hi:[0,1,0]
	v_pk_fma_f32 v[2:3], v[2:3], v[32:33], v[6:7] op_sel_hi:[0,1,1]
	s_waitcnt lgkmcnt(5)
	v_pk_fma_f32 v[22:23], v[10:11], v[24:25], v[22:23] op_sel_hi:[0,1,1]
	s_waitcnt lgkmcnt(1)
	v_pk_fma_f32 v[2:3], v[10:11], v[30:31], v[2:3] op_sel_hi:[0,1,1]
	v_pk_fma_f32 v[22:23], v[4:5], v[28:29], v[22:23] op_sel_hi:[0,1,1]
	s_waitcnt lgkmcnt(0)
	v_pk_fma_f32 v[2:3], v[4:5], v[34:35], v[2:3] op_sel_hi:[0,1,1]
	v_pk_mul_f32 v[8:9], v[8:9], v[0:1] op_sel_hi:[1,0]
	v_pk_mul_f32 v[12:13], v[0:1], v[12:13] op_sel_hi:[0,1]
	v_pk_mul_f32 v[14:15], v[0:1], v[14:15] op_sel_hi:[0,1]
	v_pk_mul_f32 v[16:17], v[0:1], v[16:17] op_sel_hi:[0,1]
	v_pk_mul_f32 v[18:19], v[0:1], v[18:19] op_sel_hi:[0,1]
	v_pk_mul_f32 v[20:21], v[0:1], v[20:21] op_sel_hi:[0,1]
	v_pk_mul_f32 v[22:23], v[0:1], v[22:23] op_sel_hi:[0,1]
	v_pk_mul_f32 v[2:3], v[0:1], v[2:3] op_sel_hi:[0,1]
	v_lshlrev_b32_e32 v0, 11, v175
	v_lshl_or_b32 v0, v82, 16, v0
	v_lshlrev_b32_e32 v6, 5, v177
	v_lshl_add_u64 v[4:5], s[38:39], 0, v[0:1]
	v_ashrrev_i32_e32 v7, 31, v6
	v_lshl_add_u64 v[4:5], v[6:7], 1, v[4:5]
	v_mov_b32_e32 v177, v1
	v_lshl_add_u64 v[4:5], v[4:5], 0, v[176:177]
	s_mov_b64 s[4:5], 0x4328400
	v_lshl_add_u64 v[6:7], v[4:5], 0, s[4:5]
	s_mov_b32 s4, 0x4328000
	v_add_co_u32_e32 v4, vcc, s4, v4
	v_cvt_pk_bf16_f32 v8, v8, v9
	v_cvt_pk_bf16_f32 v9, v12, v13
	v_addc_co_u32_e32 v5, vcc, 0, v5, vcc
	global_store_dwordx2 v[4:5], v[8:9], off offset:1024
	v_cvt_pk_bf16_f32 v4, v14, v15
	v_cvt_pk_bf16_f32 v5, v16, v17
	global_store_dwordx2 v[6:7], v[4:5], off offset:16
	v_cvt_pk_bf16_f32 v4, v18, v19
	v_cvt_pk_bf16_f32 v5, v20, v21
	global_store_dwordx2 v[6:7], v[4:5], off offset:32
	v_cvt_pk_bf16_f32 v4, v22, v23
	v_cvt_pk_bf16_f32 v5, v2, v3
	global_store_dwordx2 v[6:7], v[4:5], off offset:48
	s_barrier
	s_mov_b64 s[14:15], 0

.LBB0_592:
	s_cmp_lt_u32 s14, s7
	s_cselect_b32 s4, 0, s7
	s_cselect_b32 s5, s24, s1
	s_lshl_b32 s4, s4, 5
	s_sub_i32 s4, s5, s4
	s_add_i32 s30, s15, s4
	s_add_i32 s4, s10, s14
	v_add_u32_e32 v66, s30, v158
	s_cmp_lt_u32 s4, s7
	v_ashrrev_i32_e32 v67, 31, v66
	s_cselect_b32 s4, 0, s7
	v_lshlrev_b64 v[66:67], 9, v[66:67]
	s_cselect_b32 s5, s24, s1
	s_lshl_b32 s4, s4, 5
	v_add_u32_e32 v166, 0x8800, v161
	v_add_u32_e32 v167, 0xac00, v161
	v_add_u32_e32 v168, 0xd000, v161
	v_add_u32_e32 v169, 0xf400, v161
	v_lshl_add_u64 v[66:67], v[150:151], 0, v[66:67]
	s_sub_i32 s4, s5, s4
	s_add_i32 s5, s20, s15
	s_waitcnt vmcnt(7)
	ds_write_b128 v160, v[118:121]
	s_waitcnt vmcnt(6)
	ds_write2_b64 v166, v[114:115], v[116:117] offset1:1
	s_waitcnt vmcnt(5)
	ds_write_b128 v160, v[126:129] offset:8704
	s_waitcnt vmcnt(4)
	ds_write2_b64 v167, v[122:123], v[124:125] offset1:1
	s_waitcnt vmcnt(3)
	ds_write_b128 v160, v[134:137] offset:17408
	s_waitcnt vmcnt(2)
	ds_write2_b64 v168, v[130:131], v[132:133] offset1:1
	s_waitcnt vmcnt(1)
	ds_write_b128 v160, v[142:145] offset:26112
	s_waitcnt vmcnt(0)
	ds_write2_b64 v169, v[138:139], v[140:141] offset1:1
	s_waitcnt lgkmcnt(0)
	s_barrier
	global_load_dwordx4 v[118:121], v[66:67], off
	v_lshl_add_u64 v[66:67], s[30:31], 1, v[152:153]
	s_add_i32 s30, s5, s4
	s_add_i32 s4, s4, s15
	global_load_dwordx4 v[114:117], v[66:67], off
	v_add_u32_e32 v66, s4, v164
	s_add_i32 s4, s11, s14
	s_cmp_lt_u32 s4, s7
	v_ashrrev_i32_e32 v67, 31, v66
	s_cselect_b32 s4, 0, s7
	v_lshlrev_b64 v[66:67], 9, v[66:67]
	s_cselect_b32 s5, s24, s1
	s_lshl_b32 s4, s4, 5
	v_lshl_add_u64 v[66:67], v[150:151], 0, v[66:67]
	s_sub_i32 s4, s5, s4
	s_add_i32 s5, s21, s15
	global_load_dwordx4 v[126:129], v[66:67], off
	v_lshl_add_u64 v[66:67], s[30:31], 1, v[152:153]
	s_add_i32 s30, s5, s4
	s_add_i32 s4, s4, s15
	global_load_dwordx4 v[122:125], v[66:67], off
	v_add_u32_e32 v66, s4, v162
	s_add_i32 s4, s18, s14
	s_cmp_lt_u32 s4, s7
	v_ashrrev_i32_e32 v67, 31, v66
	s_cselect_b32 s4, 0, s7
	v_lshlrev_b64 v[66:67], 9, v[66:67]
	s_cselect_b32 s5, s24, s1
	s_lshl_b32 s4, s4, 5
	v_lshl_add_u64 v[66:67], v[150:151], 0, v[66:67]
	s_sub_i32 s4, s5, s4
	s_add_i32 s5, s19, s15
	global_load_dwordx4 v[134:137], v[66:67], off
	v_lshl_add_u64 v[66:67], s[30:31], 1, v[152:153]
	s_add_i32 s30, s5, s4
	s_add_i32 s4, s4, s15
	global_load_dwordx4 v[130:133], v[66:67], off
	v_add_u32_e32 v66, s4, v163
	v_ashrrev_i32_e32 v67, 31, v66
	v_lshlrev_b64 v[66:67], 9, v[66:67]
	v_lshl_add_u64 v[66:67], v[150:151], 0, v[66:67]
	global_load_dwordx4 v[142:145], v[66:67], off
	v_lshl_add_u64 v[66:67], s[30:31], 1, v[152:153]
	global_load_dwordx4 v[138:141], v[66:67], off
	ds_read_b128 v[66:69], v159
	ds_read_b128 v[176:179], v159 offset:32
	s_waitcnt lgkmcnt(1)
	v_mfma_f32_32x32x16_bf16 v[66:81], v[66:69], v[110:113], 0
	v_mov_b32_e32 v0, v149
	v_mov_b32_e32 v175, v148
	s_add_i32 s15, s15, 32
	s_add_i32 s14, s14, 1
	s_cmp_lg_u32 s20, s15
	s_waitcnt lgkmcnt(0)
	v_mfma_f32_32x32x16_bf16 v[66:81], v[176:179], v[106:109], v[66:81]
	ds_read_b128 v[176:179], v159 offset:64
	s_waitcnt lgkmcnt(0)
	v_mfma_f32_32x32x16_bf16 v[66:81], v[176:179], v[102:105], v[66:81]
	ds_read_b128 v[176:179], v159 offset:96
	s_waitcnt lgkmcnt(0)
	v_mfma_f32_32x32x16_bf16 v[66:81], v[176:179], v[98:101], v[66:81]
	ds_read_b128 v[176:179], v159 offset:128
	s_waitcnt lgkmcnt(0)
	v_mfma_f32_32x32x16_bf16 v[66:81], v[176:179], v[94:97], v[66:81]
	ds_read_b128 v[176:179], v159 offset:160
	s_waitcnt lgkmcnt(0)
	v_mfma_f32_32x32x16_bf16 v[66:81], v[176:179], v[90:93], v[66:81]
	ds_read_b128 v[176:179], v159 offset:192
	s_waitcnt lgkmcnt(0)
	v_mfma_f32_32x32x16_bf16 v[66:81], v[176:179], v[86:89], v[66:81]
	ds_read_b128 v[176:179], v159 offset:224
	s_waitcnt lgkmcnt(0)
	v_mfma_f32_32x32x16_bf16 v[66:81], v[176:179], v[82:85], v[66:81]
	s_nop 11
	v_max_f32_e32 v148, v67, v67
	v_max_f32_e32 v149, v66, v66
	v_max_f32_e32 v148, v149, v148
	v_max3_f32 v148, v148, v68, v69
	v_max3_f32 v148, v148, v70, v71
	v_max3_f32 v148, v148, v72, v73
	v_max3_f32 v148, v148, v74, v75
	v_max3_f32 v148, v148, v76, v77
	v_max3_f32 v148, v148, v78, v79
	v_max3_f32 v148, v148, v80, v81
	ds_bpermute_b32 v149, v156, v148
	s_waitcnt lgkmcnt(0)
	v_max3_f32 v149, v0, v148, v149
	v_mov_b32_e32 v148, v81
	v_pk_mul_f32 v[176:177], v[148:149], s[28:29] op_sel_hi:[1,0]
	v_sub_f32_e32 v0, v0, v149
	v_fma_f32 v70, v70, s28, -v177
	v_exp_f32_e32 v81, v70
	v_fma_f32 v70, v71, s28, -v177
	v_exp_f32_e32 v178, v70
	v_fma_f32 v70, v72, s28, -v177
	v_exp_f32_e32 v179, v70
	v_fma_f32 v70, v73, s28, -v177
	v_exp_f32_e32 v73, v70
	v_fma_f32 v70, v74, s28, -v177
	v_exp_f32_e32 v74, v70
	v_fma_f32 v70, v75, s28, -v177
	v_exp_f32_e32 v75, v70
	v_fma_f32 v70, v76, s28, -v177
	v_fma_f32 v66, v66, s28, -v177
	v_exp_f32_e32 v76, v70
	v_fma_f32 v70, v77, s28, -v177
	v_exp_f32_e32 v66, v66
	v_fma_f32 v67, v67, s28, -v177
	v_exp_f32_e32 v77, v70
	v_fma_f32 v70, v78, s28, -v177
	v_exp_f32_e32 v67, v67
	v_fma_f32 v68, v68, s28, -v177
	v_exp_f32_e32 v78, v70
	v_fma_f32 v70, v79, s28, -v177
	v_exp_f32_e32 v68, v68
	v_fma_f32 v69, v69, s28, -v177
	v_exp_f32_e32 v79, v70
	v_fma_f32 v70, v80, s28, -v177
	v_exp_f32_e32 v69, v69
	v_exp_f32_e32 v80, v70
	v_sub_f32_e32 v70, v176, v177
	v_exp_f32_e32 v176, v70
	v_add_f32_e32 v70, 0, v66
	v_add_f32_e32 v70, v67, v70
	v_add_f32_e32 v70, v68, v70
	v_add_f32_e32 v70, v69, v70
	v_add_f32_e32 v70, v81, v70
	v_add_f32_e32 v70, v178, v70
	v_add_f32_e32 v70, v179, v70
	v_add_f32_e32 v70, v73, v70
	v_add_f32_e32 v70, v74, v70
	v_add_f32_e32 v70, v75, v70
	v_add_f32_e32 v70, v76, v70
	v_add_f32_e32 v70, v77, v70
	v_add_f32_e32 v70, v78, v70
	v_mul_f32_e32 v0, 0x3e0293ee, v0
	v_add_f32_e32 v70, v79, v70
	v_exp_f32_e32 v0, v0
	v_add_f32_e32 v70, v80, v70
	v_cvt_pk_bf16_f32 v73, v179, v73
	v_add_u32_e32 v179, 0x8800, v165
	v_add_f32_e32 v148, v176, v70
	v_cvt_pk_bf16_f32 v70, v66, v67
	v_cvt_pk_bf16_f32 v71, v68, v69
	v_cvt_pk_bf16_f32 v72, v81, v178
	v_cvt_pk_bf16_f32 v66, v74, v75
	v_cvt_pk_bf16_f32 v67, v76, v77
	v_cvt_pk_bf16_f32 v68, v78, v79
	v_cvt_pk_bf16_f32 v69, v80, v176
	ds_read2_b64 v[74:77], v179 offset1:2
	ds_read2_b64 v[78:81], v179 offset0:4 offset1:6
	v_mul_f32_e32 v64, v0, v64
	v_mul_f32_e32 v65, v0, v65
	v_mul_f32_e32 v62, v0, v62
	v_mul_f32_e32 v63, v0, v63
	v_mul_f32_e32 v60, v0, v60
	v_mul_f32_e32 v61, v0, v61
	v_mul_f32_e32 v58, v0, v58
	v_mul_f32_e32 v59, v0, v59
	v_mul_f32_e32 v56, v0, v56
	v_mul_f32_e32 v57, v0, v57
	v_mul_f32_e32 v54, v0, v54
	v_mul_f32_e32 v55, v0, v55
	v_mul_f32_e32 v52, v0, v52
	v_mul_f32_e32 v53, v0, v53
	v_mul_f32_e32 v50, v0, v50
	v_mul_f32_e32 v51, v0, v51
	v_add_u32_e32 v176, 0x9000, v165
	v_mul_f32_e32 v48, v0, v48
	v_mul_f32_e32 v49, v0, v49
	s_waitcnt lgkmcnt(1)
	v_mfma_f32_32x32x16_bf16 v[50:65], v[74:77], v[70:73], v[50:65]
	ds_read2_b64 v[74:77], v176 offset0:32 offset1:34
	v_mul_f32_e64 v46, v46, v0
	v_mul_f32_e64 v47, v47, v0
	v_mul_f32_e64 v44, v44, v0
	v_mul_f32_e64 v45, v45, v0
	v_mul_f32_e32 v42, v0, v42
	v_mul_f32_e32 v43, v0, v43
	v_mul_f32_e32 v40, v0, v40
	v_mul_f32_e32 v41, v0, v41
	v_mul_f32_e32 v38, v0, v38
	v_mul_f32_e32 v39, v0, v39
	v_mul_f32_e32 v36, v0, v36
	v_mul_f32_e32 v37, v0, v37
	v_mul_f32_e32 v34, v0, v34
	v_mul_f32_e32 v35, v0, v35
	v_add_u32_e32 v177, 0x9800, v165
	v_mul_f32_e32 v32, v0, v32
	v_mul_f32_e32 v33, v0, v33
	s_waitcnt lgkmcnt(0)
	v_mfma_f32_32x32x16_bf16 v[34:49], v[74:77], v[70:73], v[34:49]
	ds_read2_b64 v[74:77], v176 offset0:36 offset1:38
	v_mul_f32_e64 v30, v30, v0
	v_mul_f32_e64 v31, v31, v0
	v_mul_f32_e64 v28, v28, v0
	v_mul_f32_e64 v29, v29, v0
	v_mul_f32_e32 v26, v0, v26
	v_mul_f32_e32 v27, v0, v27
	v_mul_f32_e32 v24, v0, v24
	v_mul_f32_e32 v25, v0, v25
	v_mul_f32_e32 v22, v0, v22
	v_mul_f32_e32 v23, v0, v23
	v_mul_f32_e32 v20, v0, v20
	v_mul_f32_e32 v21, v0, v21
	s_waitcnt lgkmcnt(0)
	v_mfma_f32_32x32x16_bf16 v[34:49], v[74:77], v[66:69], v[34:49]
	ds_read2_b64 v[74:77], v177 offset0:64 offset1:66
	v_mul_f32_e64 v18, v18, v0
	v_mul_f32_e64 v19, v19, v0
	v_add_u32_e32 v178, 0xa000, v165
	v_mul_f32_e64 v16, v16, v0
	v_mul_f32_e64 v17, v17, v0
	v_mul_f32_e32 v14, v0, v14
	v_mul_f32_e32 v15, v0, v15
	v_mul_f32_e32 v12, v0, v12
	v_mul_f32_e32 v13, v0, v13
	v_mul_f32_e32 v10, v0, v10
	v_mul_f32_e32 v11, v0, v11
	s_waitcnt lgkmcnt(0)
	v_mfma_f32_32x32x16_bf16 v[18:33], v[74:77], v[70:73], v[18:33]
	ds_read2_b64 v[74:77], v177 offset0:68 offset1:70
	v_mul_f32_e64 v8, v8, v0
	v_mul_f32_e64 v9, v9, v0
	v_mul_f32_e64 v6, v6, v0
	v_mul_f32_e64 v7, v7, v0
	v_mul_f32_e32 v4, v0, v4
	v_mul_f32_e32 v5, v0, v5
	v_mul_f32_e32 v2, v0, v2
	v_mul_f32_e32 v3, v0, v3
	v_fmac_f32_e32 v148, v175, v0
	s_waitcnt lgkmcnt(0)
	v_mfma_f32_32x32x16_bf16 v[18:33], v[74:77], v[66:69], v[18:33]
	ds_read2_b64 v[74:77], v178 offset0:96 offset1:98
	s_waitcnt lgkmcnt(0)
	v_mfma_f32_32x32x16_bf16 v[2:17], v[74:77], v[70:73], v[2:17]
	ds_read2_b64 v[70:73], v178 offset0:100 offset1:102
	s_waitcnt lgkmcnt(0)
	s_barrier
	v_mfma_f32_32x32x16_bf16 v[50:65], v[78:81], v[66:69], v[50:65]
	v_mfma_f32_32x32x16_bf16 v[2:17], v[70:73], v[66:69], v[2:17]
	s_cbranch_scc1 .LBB0_592
	s_waitcnt vmcnt(7)
	ds_write_b128 v160, v[118:121]
	s_waitcnt vmcnt(6)
	ds_write2_b64 v166, v[114:115], v[116:117] offset1:1
	s_waitcnt vmcnt(5)
	ds_write_b128 v160, v[126:129] offset:8704
	s_waitcnt vmcnt(4)
	ds_write2_b64 v167, v[122:123], v[124:125] offset1:1
	s_waitcnt vmcnt(3)
	ds_write_b128 v160, v[134:137] offset:17408
	s_waitcnt vmcnt(2)
	ds_write2_b64 v168, v[130:131], v[132:133] offset1:1
	s_waitcnt vmcnt(1)
	ds_write_b128 v160, v[142:145] offset:26112
	s_waitcnt vmcnt(0)
	ds_write2_b64 v169, v[138:139], v[140:141] offset1:1
	s_waitcnt lgkmcnt(0)
	s_barrier
	ds_read_b128 v[66:69], v159
	ds_read_b128 v[114:117], v159 offset:32
	s_waitcnt lgkmcnt(1)
	v_mfma_f32_32x32x16_bf16 v[66:81], v[66:69], v[110:113], 0
	v_readlane_b32 s1, v253, 17
	s_mov_b32 s4, 0xf149f2ca
	s_waitcnt lgkmcnt(0)
	v_mfma_f32_32x32x16_bf16 v[66:81], v[114:117], v[106:109], v[66:81]
	ds_read_b128 v[106:109], v159 offset:64
	ds_read_b128 v[110:113], v159 offset:96
	s_waitcnt lgkmcnt(1)
	v_mfma_f32_32x32x16_bf16 v[66:81], v[106:109], v[102:105], v[66:81]
	s_waitcnt lgkmcnt(0)
	v_mfma_f32_32x32x16_bf16 v[66:81], v[110:113], v[98:101], v[66:81]
	ds_read_b128 v[98:101], v159 offset:128
	ds_read_b128 v[102:105], v159 offset:160
	s_waitcnt lgkmcnt(1)
	v_mfma_f32_32x32x16_bf16 v[66:81], v[98:101], v[94:97], v[66:81]
	v_ashrrev_i32_e32 v100, 6, v157
	s_waitcnt lgkmcnt(0)
	v_mfma_f32_32x32x16_bf16 v[66:81], v[102:105], v[90:93], v[66:81]
	ds_read_b128 v[90:93], v159 offset:192
	ds_read_b128 v[94:97], v159 offset:224
	s_waitcnt lgkmcnt(1)
	v_mfma_f32_32x32x16_bf16 v[66:81], v[90:93], v[86:89], v[66:81]
	ds_read2_b64 v[86:89], v179 offset1:2
	s_waitcnt lgkmcnt(1)
	v_mfma_f32_32x32x16_bf16 v[66:81], v[94:97], v[82:85], v[66:81]
	ds_read2_b64 v[90:93], v179 offset0:4 offset1:6
	ds_read2_b64 v[94:97], v176 offset0:32 offset1:34
	s_nop 9
	v_max_f32_e32 v0, v67, v67
	v_max_f32_e32 v82, v66, v66
	v_max_f32_e32 v0, v82, v0
	v_max3_f32 v0, v0, v68, v69
	v_max3_f32 v0, v0, v70, v71
	v_max3_f32 v0, v0, v72, v73
	v_max3_f32 v0, v0, v74, v75
	v_max3_f32 v0, v0, v76, v77
	v_max3_f32 v0, v0, v78, v79
	v_max3_f32 v0, v0, v80, v81
	ds_bpermute_b32 v83, v156, v0
	v_mov_b32_e32 v84, v81
	v_and_b32_e32 v82, 1, v100
	s_waitcnt lgkmcnt(0)
	v_max3_f32 v85, v149, v0, v83
	v_sub_f32_e32 v0, v149, v85
	v_pk_mul_f32 v[98:99], v[84:85], s[28:29] op_sel_hi:[1,0]
	v_mul_f32_e32 v0, 0x3e0293ee, v0
	v_fma_f32 v66, v66, s28, -v99
	v_fma_f32 v67, v67, s28, -v99
	v_fma_f32 v68, v68, s28, -v99
	v_fma_f32 v69, v69, s28, -v99
	v_fma_f32 v70, v70, s28, -v99
	v_fma_f32 v71, v71, s28, -v99
	v_fma_f32 v72, v72, s28, -v99
	v_fma_f32 v73, v73, s28, -v99
	v_fma_f32 v74, v74, s28, -v99
	v_fma_f32 v75, v75, s28, -v99
	v_fma_f32 v76, v76, s28, -v99
	v_fma_f32 v77, v77, s28, -v99
	v_fma_f32 v78, v78, s28, -v99
	v_fma_f32 v79, v79, s28, -v99
	v_fma_f32 v80, v80, s28, -v99
	v_sub_f32_e32 v81, v98, v99
	v_exp_f32_e32 v0, v0
	v_exp_f32_e32 v83, v66
	v_exp_f32_e32 v84, v67
	v_exp_f32_e32 v98, v68
	v_exp_f32_e32 v99, v69
	v_exp_f32_e32 v101, v70
	v_exp_f32_e32 v102, v71
	v_exp_f32_e32 v103, v72
	v_exp_f32_e32 v104, v73
	v_exp_f32_e32 v105, v74
	v_exp_f32_e32 v106, v75
	v_exp_f32_e32 v107, v76
	v_exp_f32_e32 v108, v77
	v_pk_mul_f32 v[48:49], v[48:49], v[0:1] op_sel_hi:[1,0]
	v_pk_mul_f32 v[46:47], v[46:47], v[0:1] op_sel_hi:[1,0]
	v_cvt_pk_bf16_f32 v66, v83, v84
	v_cvt_pk_bf16_f32 v67, v98, v99
	v_cvt_pk_bf16_f32 v68, v101, v102
	v_cvt_pk_bf16_f32 v69, v103, v104
	v_pk_mul_f32 v[44:45], v[44:45], v[0:1] op_sel_hi:[1,0]
	v_pk_mul_f32 v[42:43], v[42:43], v[0:1] op_sel_hi:[1,0]
	v_pk_mul_f32 v[40:41], v[40:41], v[0:1] op_sel_hi:[1,0]
	v_pk_mul_f32 v[38:39], v[38:39], v[0:1] op_sel_hi:[1,0]
	v_pk_mul_f32 v[36:37], v[36:37], v[0:1] op_sel_hi:[1,0]
	v_pk_mul_f32 v[34:35], v[34:35], v[0:1] op_sel_hi:[1,0]
	ds_read2_b64 v[74:77], v176 offset0:36 offset1:38
	v_exp_f32_e32 v109, v78
	v_exp_f32_e32 v110, v79
	v_exp_f32_e32 v111, v80
	v_exp_f32_e32 v112, v81
	v_mfma_f32_32x32x16_bf16 v[34:49], v[94:97], v[66:69], v[34:49]
	ds_read2_b64 v[78:81], v177 offset0:64 offset1:66
	v_cvt_pk_bf16_f32 v70, v105, v106
	v_cvt_pk_bf16_f32 v71, v107, v108
	v_cvt_pk_bf16_f32 v72, v109, v110
	v_cvt_pk_bf16_f32 v73, v111, v112
	v_pk_mul_f32 v[32:33], v[32:33], v[0:1] op_sel_hi:[1,0]
	v_pk_mul_f32 v[30:31], v[30:31], v[0:1] op_sel_hi:[1,0]
	v_pk_mul_f32 v[28:29], v[28:29], v[0:1] op_sel_hi:[1,0]
	v_pk_mul_f32 v[26:27], v[26:27], v[0:1] op_sel_hi:[1,0]
	v_pk_mul_f32 v[24:25], v[24:25], v[0:1] op_sel_hi:[1,0]
	v_pk_mul_f32 v[22:23], v[22:23], v[0:1] op_sel_hi:[1,0]
	v_pk_mul_f32 v[20:21], v[20:21], v[0:1] op_sel_hi:[1,0]
	v_pk_mul_f32 v[18:19], v[18:19], v[0:1] op_sel_hi:[1,0]
	s_waitcnt lgkmcnt(1)
	v_mfma_f32_32x32x16_bf16 v[34:49], v[74:77], v[70:73], v[34:49]
	ds_read2_b64 v[74:77], v177 offset0:68 offset1:70
	v_mul_f32_e64 v64, v64, v0
	v_mul_f32_e64 v65, v65, v0
	v_mul_f32_e64 v62, v62, v0
	v_mul_f32_e64 v63, v63, v0
	v_pk_mul_f32 v[60:61], v[60:61], v[0:1] op_sel_hi:[1,0]
	v_pk_mul_f32 v[58:59], v[58:59], v[0:1] op_sel_hi:[1,0]
	v_pk_mul_f32 v[56:57], v[56:57], v[0:1] op_sel_hi:[1,0]
	v_pk_mul_f32 v[54:55], v[54:55], v[0:1] op_sel_hi:[1,0]
	s_waitcnt lgkmcnt(1)
	v_mfma_f32_32x32x16_bf16 v[18:33], v[78:81], v[66:69], v[18:33]
	v_add_f32_e32 v78, 0, v83
	v_add_f32_e32 v78, v84, v78
	v_add_f32_e32 v78, v98, v78
	v_add_f32_e32 v78, v99, v78
	v_add_f32_e32 v83, v101, v78
	ds_read2_b64 v[78:81], v178 offset0:96 offset1:98
	v_pk_mul_f32 v[52:53], v[52:53], v[0:1] op_sel_hi:[1,0]
	s_waitcnt lgkmcnt(1)
	v_mfma_f32_32x32x16_bf16 v[18:33], v[74:77], v[70:73], v[18:33]
	v_add_f32_e32 v74, v102, v83
	v_add_f32_e32 v74, v103, v74
	v_add_f32_e32 v74, v104, v74
	v_add_f32_e32 v74, v105, v74
	v_mul_f32_e64 v50, v50, v0
	v_mul_f32_e64 v51, v51, v0
	v_add_f32_e32 v74, v106, v74
	v_pk_mul_f32 v[16:17], v[16:17], v[0:1] op_sel_hi:[1,0]
	v_mfma_f32_32x32x16_bf16 v[50:65], v[86:89], v[66:69], v[50:65]
	v_mul_f32_e64 v14, v14, v0
	v_mul_f32_e64 v15, v15, v0
	v_mul_f32_e64 v12, v12, v0
	v_mul_f32_e64 v13, v13, v0
	v_mul_f32_e64 v10, v10, v0
	v_mul_f32_e64 v11, v11, v0
	v_pk_mul_f32 v[8:9], v[8:9], v[0:1] op_sel_hi:[1,0]
	v_pk_mul_f32 v[6:7], v[6:7], v[0:1] op_sel_hi:[1,0]
	v_pk_mul_f32 v[4:5], v[4:5], v[0:1] op_sel_hi:[1,0]
	v_pk_mul_f32 v[2:3], v[2:3], v[0:1] op_sel_hi:[1,0]
	v_add_f32_e32 v83, v107, v74
	ds_read2_b64 v[74:77], v178 offset0:100 offset1:102
	s_waitcnt lgkmcnt(1)
	v_mfma_f32_32x32x16_bf16 v[2:17], v[78:81], v[66:69], v[2:17]
	v_add_f32_e32 v66, v108, v83
	v_add_f32_e32 v66, v109, v66
	v_add_f32_e32 v66, v110, v66
	v_add_f32_e32 v66, v111, v66
	v_add_f32_e32 v66, v112, v66
	v_fmac_f32_e32 v66, v148, v0
	ds_bpermute_b32 v0, v156, v66
	v_mfma_f32_32x32x16_bf16 v[50:65], v[90:93], v[70:73], v[50:65]
	v_lshlrev_b32_e32 v67, 2, v155
	s_waitcnt lgkmcnt(0)
	s_barrier
	v_add_f32_e32 v0, v66, v0
	v_lshlrev_b32_e32 v66, 9, v100
	v_add3_u32 v66, s1, v66, v67
	ds_write2st64_b32 v66, v85, v0 offset1:1
	v_lshlrev_b32_e32 v0, 14, v100
	v_add3_u32 v0, 0, v0, v67
	v_mfma_f32_32x32x16_bf16 v[2:17], v[74:77], v[70:73], v[2:17]
	s_nop 1
	ds_write2st64_b32 v0, v50, v51 offset1:1
	ds_write2st64_b32 v0, v52, v53 offset0:2 offset1:3
	ds_write2st64_b32 v0, v54, v55 offset0:4 offset1:5
	ds_write2st64_b32 v0, v56, v57 offset0:6 offset1:7
	ds_write2st64_b32 v0, v58, v59 offset0:8 offset1:9
	ds_write2st64_b32 v0, v60, v61 offset0:10 offset1:11
	ds_write2st64_b32 v0, v62, v63 offset0:12 offset1:13
	ds_write2st64_b32 v0, v64, v65 offset0:14 offset1:15
	ds_write2st64_b32 v0, v34, v35 offset0:16 offset1:17
	ds_write2st64_b32 v0, v36, v37 offset0:18 offset1:19
	ds_write2st64_b32 v0, v38, v39 offset0:20 offset1:21
	ds_write2st64_b32 v0, v40, v41 offset0:22 offset1:23
	ds_write2st64_b32 v0, v42, v43 offset0:24 offset1:25
	ds_write2st64_b32 v0, v44, v45 offset0:26 offset1:27
	ds_write2st64_b32 v0, v46, v47 offset0:28 offset1:29
	ds_write2st64_b32 v0, v48, v49 offset0:30 offset1:31
	ds_write2st64_b32 v0, v18, v19 offset0:32 offset1:33
	ds_write2st64_b32 v0, v20, v21 offset0:34 offset1:35
	ds_write2st64_b32 v0, v22, v23 offset0:36 offset1:37
	ds_write2st64_b32 v0, v24, v25 offset0:38 offset1:39
	ds_write2st64_b32 v0, v26, v27 offset0:40 offset1:41
	ds_write2st64_b32 v0, v28, v29 offset0:42 offset1:43
	ds_write2st64_b32 v0, v30, v31 offset0:44 offset1:45
	ds_write2st64_b32 v0, v32, v33 offset0:46 offset1:47
	ds_write2st64_b32 v0, v2, v3 offset0:48 offset1:49
	ds_write2st64_b32 v0, v4, v5 offset0:50 offset1:51
	ds_write2st64_b32 v0, v6, v7 offset0:52 offset1:53
	ds_write2st64_b32 v0, v8, v9 offset0:54 offset1:55
	ds_write2st64_b32 v0, v10, v11 offset0:56 offset1:57
	ds_write2st64_b32 v0, v12, v13 offset0:58 offset1:59
	ds_write2st64_b32 v0, v14, v15 offset0:60 offset1:61
	ds_write2st64_b32 v0, v16, v17 offset0:62 offset1:63
	v_lshlrev_b32_e32 v0, 9, v82
	v_add3_u32 v0, s1, v0, v67
	s_waitcnt lgkmcnt(0)
	s_barrier
	ds_read2st64_b32 v[4:5], v0 offset1:1
	ds_read2st64_b32 v[6:7], v0 offset0:4 offset1:5
	ds_read2st64_b32 v[8:9], v0 offset0:8 offset1:9
	ds_read2st64_b32 v[10:11], v0 offset0:12 offset1:13
	s_mov_b32 s1, s31
	s_lshl_b64 s[0:1], s[0:1], 11
	s_waitcnt lgkmcnt(2)
	v_max3_f32 v0, v4, s4, v6
	s_add_u32 s4, s80, s0
	s_waitcnt lgkmcnt(0)
	v_max3_f32 v0, v0, v8, v10
	v_sub_f32_e32 v2, v4, v0
	v_mul_f32_e32 v2, 0x3e0293ee, v2
	v_exp_f32_e32 v3, v2
	v_sub_f32_e32 v2, v6, v0
	v_mul_f32_e32 v2, 0x3e0293ee, v2
	v_exp_f32_e32 v2, v2
	v_mov_b32_e32 v4, v7
	s_addc_u32 s5, s81, s1
	v_pk_mul_f32 v[6:7], v[4:5], v[2:3]
	v_sub_f32_e32 v4, v8, v0
	v_sub_f32_e32 v0, v10, v0
	v_mul_f32_e32 v4, 0x3e0293ee, v4
	v_mul_f32_e32 v0, 0x3e0293ee, v0
	v_exp_f32_e32 v5, v4
	v_exp_f32_e32 v4, v0
	v_add_f32_e32 v0, 0, v7
	v_mov_b32_e32 v8, v11
	v_add_f32_e32 v0, v6, v0
	v_pk_mul_f32 v[6:7], v[8:9], v[4:5]
	s_nop 0
	v_add_f32_e32 v0, v7, v0
	v_add_f32_e32 v0, v6, v0
	v_div_scale_f32 v6, s[0:1], v0, v0, 1.0
	v_rcp_f32_e32 v7, v6
	s_lshl_b32 s0, s6, 1
	s_add_u32 s0, s4, s0
	s_addc_u32 s1, s5, 0
	v_fma_f32 v8, -v6, v7, 1.0
	v_fmac_f32_e32 v7, v8, v7
	v_div_scale_f32 v8, vcc, 1.0, v0, 1.0
	v_mul_f32_e32 v9, v8, v7
	v_fma_f32 v10, -v6, v9, v8
	v_fmac_f32_e32 v9, v10, v7
	v_fma_f32 v6, -v6, v9, v8
	v_div_fmas_f32 v6, v6, v7, v9
	v_div_fixup_f32 v0, v6, v0, 1.0
	v_lshl_add_u32 v6, v82, 14, 0
	v_lshlrev_b32_e32 v7, 12, v154
	v_add3_u32 v7, v6, v7, v67
	ds_read2st64_b32 v[8:9], v7 offset1:1
	ds_read2st64_b32 v[10:11], v7 offset0:128 offset1:129
	v_mov_b32_e32 v6, v3
	v_add_u32_e32 v24, 0x10000, v7
	v_add_u32_e32 v25, 0x18000, v7
	v_add_u32_e32 v27, 0x10100, v7
	v_add_u32_e32 v28, 0x18100, v7
	ds_read2st64_b32 v[12:13], v7 offset0:2 offset1:3
	ds_read2st64_b32 v[14:15], v7 offset0:4 offset1:5
	ds_read2st64_b32 v[16:17], v7 offset0:6 offset1:7
	s_waitcnt lgkmcnt(4)
	v_pk_fma_f32 v[8:9], v[8:9], v[6:7], 0 op_sel_hi:[1,0,0]
	v_add_u32_e32 v31, 0x18300, v7
	ds_read2st64_b32 v[18:19], v7 offset0:130 offset1:131
	ds_read2st64_b32 v[20:21], v7 offset0:132 offset1:133
	ds_read2st64_b32 v[22:23], v7 offset0:134 offset1:135
	s_waitcnt lgkmcnt(6)
	v_pk_fma_f32 v[8:9], v[10:11], v[2:3], v[8:9] op_sel_hi:[1,0,1]
	v_mov_b32_e32 v10, v5
	v_add_u32_e32 v3, 0x10200, v7
	v_add_u32_e32 v5, 0x18200, v7
	v_add_u32_e32 v11, 0x10300, v7
	ds_read_b32 v24, v24
	ds_read_b32 v26, v25
	ds_read_b32 v25, v27
	ds_read_b32 v27, v28
	ds_read_b32 v28, v3
	ds_read_b32 v30, v5
	ds_read_b32 v29, v11
	ds_read_b32 v31, v31
	s_waitcnt lgkmcnt(13)
	v_pk_fma_f32 v[12:13], v[6:7], v[12:13], 0 op_sel_hi:[0,1,0]
	s_waitcnt lgkmcnt(5)
	v_pk_fma_f32 v[8:9], v[10:11], v[24:25], v[8:9] op_sel_hi:[0,1,1]
	v_pk_fma_f32 v[12:13], v[2:3], v[18:19], v[12:13] op_sel_hi:[0,1,1]
	v_add_u32_e32 v3, 0x10400, v7
	v_pk_fma_f32 v[14:15], v[6:7], v[14:15], 0 op_sel_hi:[0,1,0]
	s_waitcnt lgkmcnt(4)
	v_pk_fma_f32 v[8:9], v[4:5], v[26:27], v[8:9] op_sel_hi:[0,1,1]
	s_waitcnt lgkmcnt(1)
	v_pk_fma_f32 v[12:13], v[10:11], v[28:29], v[12:13] op_sel_hi:[0,1,1]
	v_add_u32_e32 v11, 0x10500, v7
	v_add_u32_e32 v24, 0x18500, v7
	v_pk_fma_f32 v[14:15], v[2:3], v[20:21], v[14:15] op_sel_hi:[0,1,1]
	v_add_u32_e32 v25, 0x10600, v7
	v_add_u32_e32 v26, 0x18600, v7
	v_add_u32_e32 v27, 0x10700, v7
	s_waitcnt lgkmcnt(0)
	v_pk_fma_f32 v[12:13], v[4:5], v[30:31], v[12:13] op_sel_hi:[0,1,1]
	v_add_u32_e32 v5, 0x18400, v7
	v_add_u32_e32 v28, 0x18700, v7
	ds_read_b32 v18, v3
	ds_read_b32 v20, v5
	ds_read_b32 v19, v11
	ds_read_b32 v21, v24
	ds_read_b32 v24, v25
	ds_read_b32 v26, v26
	ds_read_b32 v25, v27
	ds_read_b32 v27, v28
	s_waitcnt lgkmcnt(5)
	v_pk_fma_f32 v[14:15], v[10:11], v[18:19], v[14:15] op_sel_hi:[0,1,1]
	s_waitcnt lgkmcnt(4)
	v_pk_fma_f32 v[14:15], v[4:5], v[20:21], v[14:15] op_sel_hi:[0,1,1]
	ds_read2st64_b32 v[18:19], v7 offset0:8 offset1:9
	ds_read2st64_b32 v[20:21], v7 offset0:136 offset1:137
	v_pk_fma_f32 v[16:17], v[6:7], v[16:17], 0 op_sel_hi:[0,1,0]
	v_pk_fma_f32 v[16:17], v[2:3], v[22:23], v[16:17] op_sel_hi:[0,1,1]
	s_waitcnt lgkmcnt(3)
	v_pk_fma_f32 v[16:17], v[10:11], v[24:25], v[16:17] op_sel_hi:[0,1,1]
	s_waitcnt lgkmcnt(2)
	v_pk_fma_f32 v[16:17], v[4:5], v[26:27], v[16:17] op_sel_hi:[0,1,1]
	v_add_u32_e32 v3, 0x10800, v7
	v_add_u32_e32 v35, 0x18900, v7
	ds_read2st64_b32 v[22:23], v7 offset0:10 offset1:11
	ds_read2st64_b32 v[24:25], v7 offset0:12 offset1:13
	ds_read2st64_b32 v[26:27], v7 offset0:14 offset1:15
	s_waitcnt lgkmcnt(4)
	v_pk_fma_f32 v[18:19], v[6:7], v[18:19], 0 op_sel_hi:[0,1,0]
	v_add_u32_e32 v36, 0x10a00, v7
	v_add_u32_e32 v37, 0x18a00, v7
	v_add_u32_e32 v39, 0x10b00, v7
	v_add_u32_e32 v5, 0x18800, v7
	v_add_u32_e32 v11, 0x10900, v7
	ds_read2st64_b32 v[28:29], v7 offset0:138 offset1:139
	ds_read2st64_b32 v[30:31], v7 offset0:140 offset1:141
	ds_read2st64_b32 v[32:33], v7 offset0:142 offset1:143
	s_waitcnt lgkmcnt(6)
	v_pk_fma_f32 v[18:19], v[2:3], v[20:21], v[18:19] op_sel_hi:[0,1,1]
	v_add_u32_e32 v40, 0x18b00, v7
	ds_read_b32 v20, v3
	ds_read_b32 v34, v5
	ds_read_b32 v21, v11
	ds_read_b32 v35, v35
	ds_read_b32 v36, v36
	ds_read_b32 v38, v37
	ds_read_b32 v37, v39
	ds_read_b32 v39, v40
	s_waitcnt lgkmcnt(5)
	v_pk_fma_f32 v[18:19], v[10:11], v[20:21], v[18:19] op_sel_hi:[0,1,1]
	v_pk_fma_f32 v[20:21], v[6:7], v[22:23], 0 op_sel_hi:[0,1,0]
	v_pk_fma_f32 v[20:21], v[2:3], v[28:29], v[20:21] op_sel_hi:[0,1,1]
	v_add_u32_e32 v3, 0x10c00, v7
	v_pk_fma_f32 v[22:23], v[6:7], v[24:25], 0 op_sel_hi:[0,1,0]
	s_waitcnt lgkmcnt(4)
	v_pk_fma_f32 v[18:19], v[4:5], v[34:35], v[18:19] op_sel_hi:[0,1,1]
	s_waitcnt lgkmcnt(1)
	v_pk_fma_f32 v[20:21], v[10:11], v[36:37], v[20:21] op_sel_hi:[0,1,1]
	v_add_u32_e32 v29, 0x18d00, v7
	v_pk_fma_f32 v[22:23], v[2:3], v[30:31], v[22:23] op_sel_hi:[0,1,1]
	v_add_u32_e32 v30, 0x10e00, v7
	v_add_u32_e32 v31, 0x18e00, v7
	v_add_u32_e32 v35, 0x10f00, v7
	s_waitcnt lgkmcnt(0)
	v_pk_fma_f32 v[20:21], v[4:5], v[38:39], v[20:21] op_sel_hi:[0,1,1]
	v_add_u32_e32 v5, 0x18c00, v7
	v_add_u32_e32 v11, 0x10d00, v7
	v_add_u32_e32 v7, 0x18f00, v7
	ds_read_b32 v24, v3
	ds_read_b32 v28, v5
	ds_read_b32 v25, v11
	ds_read_b32 v29, v29
	ds_read_b32 v30, v30
	ds_read_b32 v34, v31
	ds_read_b32 v31, v35
	ds_read_b32 v35, v7
	v_pk_fma_f32 v[6:7], v[6:7], v[26:27], 0 op_sel_hi:[0,1,0]
	v_pk_fma_f32 v[2:3], v[2:3], v[32:33], v[6:7] op_sel_hi:[0,1,1]
	s_waitcnt lgkmcnt(5)
	v_pk_fma_f32 v[22:23], v[10:11], v[24:25], v[22:23] op_sel_hi:[0,1,1]
	s_waitcnt lgkmcnt(1)
	v_pk_fma_f32 v[2:3], v[10:11], v[30:31], v[2:3] op_sel_hi:[0,1,1]
	v_pk_fma_f32 v[22:23], v[4:5], v[28:29], v[22:23] op_sel_hi:[0,1,1]
	s_waitcnt lgkmcnt(0)
	v_pk_fma_f32 v[2:3], v[4:5], v[34:35], v[2:3] op_sel_hi:[0,1,1]
	v_pk_mul_f32 v[8:9], v[8:9], v[0:1] op_sel_hi:[1,0]
	v_pk_mul_f32 v[12:13], v[0:1], v[12:13] op_sel_hi:[0,1]
	v_pk_mul_f32 v[14:15], v[0:1], v[14:15] op_sel_hi:[0,1]
	v_pk_mul_f32 v[16:17], v[0:1], v[16:17] op_sel_hi:[0,1]
	v_pk_mul_f32 v[18:19], v[0:1], v[18:19] op_sel_hi:[0,1]
	v_pk_mul_f32 v[20:21], v[0:1], v[20:21] op_sel_hi:[0,1]
	v_pk_mul_f32 v[22:23], v[0:1], v[22:23] op_sel_hi:[0,1]
	v_pk_mul_f32 v[2:3], v[0:1], v[2:3] op_sel_hi:[0,1]
	v_lshlrev_b32_e32 v0, 11, v147
	v_lshl_or_b32 v0, v82, 16, v0
	v_lshlrev_b32_e32 v6, 5, v154
	v_lshl_add_u64 v[4:5], s[0:1], 0, v[0:1]
	v_ashrrev_i32_e32 v7, 31, v6
	v_lshl_add_u64 v[4:5], v[6:7], 1, v[4:5]
	v_mov_b32_e32 v147, v1
	v_lshl_add_u64 v[4:5], v[4:5], 0, v[146:147]
	s_mov_b64 s[0:1], 0x4328400
	v_lshl_add_u64 v[6:7], v[4:5], 0, s[0:1]
	s_mov_b32 s0, 0x4328000
	v_add_co_u32_e32 v4, vcc, s0, v4
	v_cvt_pk_bf16_f32 v8, v8, v9
	v_cvt_pk_bf16_f32 v9, v12, v13
	v_addc_co_u32_e32 v5, vcc, 0, v5, vcc
	global_store_dwordx2 v[4:5], v[8:9], off offset:1024
	v_cvt_pk_bf16_f32 v4, v14, v15
	v_cvt_pk_bf16_f32 v5, v16, v17
	global_store_dwordx2 v[6:7], v[4:5], off offset:16
	v_cvt_pk_bf16_f32 v4, v18, v19
	v_cvt_pk_bf16_f32 v5, v20, v21
	global_store_dwordx2 v[6:7], v[4:5], off offset:32
	v_cvt_pk_bf16_f32 v4, v22, v23
	v_cvt_pk_bf16_f32 v5, v2, v3
	global_store_dwordx2 v[6:7], v[4:5], off offset:48
	s_barrier
	s_mov_b64 s[0:1], 0
